# barrier: st[] words read with ds_read instead of two serialized flat loads; leader no longer waits for its XGEN release atomic to complete
# speedup vs baseline: 1.0016x; 1.0016x over previous
; __device__ __forceinline__ int mk_tid(int wid_s) { int t = wid_s * 64 + (int)__builtin_amdgcn_mbcnt_hi(~0u, __builtin_amdgcn_mbcnt_lo(~0u, 0u)); asm volatile("" : "+v"(t)); return t; }
; __device__ __forceinline__ unsigned xb_ld(unsigned* p)              { return __hip_atomic_load(p, __ATOMIC_RELAXED, __HIP_MEMORY_SCOPE_AGENT); }
; __device__ __forceinline__ unsigned xb_add(unsigned* p, unsigned v) { return __hip_atomic_fetch_add(p, v, __ATOMIC_RELAXED, __HIP_MEMORY_SCOPE_AGENT); }
; __device__ __forceinline__ unsigned xb_xcc_id() { return (unsigned)__builtin_amdgcn_s_getreg((3 << 11) | 20) & 0xFu; }
; #define XB_SPIN(cond, bar) do { unsigned _sp = 0; while (cond) { \
;     if ((++_sp & 255u) == 0u) { if (xb_ld(&(bar)[XB_TMO])) break; if (_sp > XB_SPIN_CAP) { atomicAdd(&(bar)[XB_TMO], 1u); break; } } } } while (0)
; __device__ __forceinline__ void grid_barrier1(int wid_s, unsigned* bar, volatile unsigned* st) {
;     asm volatile("s_waitcnt vmcnt(0)" ::: "memory");
;     __syncthreads();
;     if (mk_tid(wid_s) == 0) {
;         const unsigned x = xb_xcc_id();
;         __builtin_amdgcn_s_waitcnt(0);
;         unsigned nloc = st[0], nx = st[1];
;         if (nloc == 0u) { xcd_barrier_complete(bar, x, nloc, nx); st[0] = nloc; st[1] = nx; }
;         const unsigned old = xb_add(&bar[XB_XSUB(x)], 1u);
;         const unsigned gen = old / nloc;
;         if (old + 1u == (gen + 1u) * nloc) {
;             __builtin_amdgcn_fence(__ATOMIC_RELEASE, "agent");
;             asm volatile("s_waitcnt vmcnt(0)" ::: "memory");
;             const unsigned og = xb_add(&bar[XB_TOP], 1u);
;             const unsigned tg = og / nx;
;             if (og + 1u == (tg + 1u) * nx) xb_add(&bar[XB_TOPGEN], 1u);
;             else XB_SPIN(xb_ld(&bar[XB_TOPGEN]) == tg, bar);
;             __builtin_amdgcn_fence(__ATOMIC_ACQUIRE, "agent");
;             xb_add(&bar[XB_XGEN(x)], 1u);
;             asm volatile("s_waitcnt vmcnt(0)" ::: "memory");
;         } else {
;             XB_SPIN(xb_ld(&bar[XB_XGEN(x)]) == gen, bar);
;             __builtin_amdgcn_fence(__ATOMIC_ACQUIRE, "agent");
;             asm volatile("s_waitcnt vmcnt(0)" ::: "memory");
;         }
;     }
;     __syncthreads();
; }
.LBB0_424:
	s_or_b64 exec, exec, s[2:3]
	v_mov_b32_e32 v0, s25
	v_add_co_u32_e32 v0, vcc, 0x2000, v0
	v_mov_b32_e32 v1, s24
	s_nop 0
	v_addc_co_u32_e32 v1, vcc, 0, v1, vcc
	s_waitcnt vmcnt(0) lgkmcnt(0)
	flat_atomic_add v[0:1], v170 offset:1024
.LBB0_425:
	s_or_b64 exec, exec, s[46:47]
	s_add_i32 s19, s19, 1
	s_cmp_lg_u32 s19, s18
	s_waitcnt lgkmcnt(0)
	s_barrier
	s_cbranch_scc0 .LBB0_7
.LBB0_426:
	s_waitcnt vmcnt(0)
	v_mov_b32_e32 v0, v169
	s_waitcnt lgkmcnt(0)
	s_barrier
	s_nop 0
	v_cmp_eq_u32_e32 vcc, 0, v0
	s_and_saveexec_b64 s[46:47], vcc
	s_cbranch_execz .LBB0_425
	s_mov_b64 s[2:3], src_shared_base
	s_getreg_b32 s2, hwreg(HW_REG_XCC_ID, 0, 4)
	s_and_b32 s33, s2, 15
	s_add_i32 s36, 0, 0x222f0
	s_cmp_lg_u32 s36, -1
	s_cselect_b32 s2, s36, 0
	s_cselect_b32 s4, s3, 0
	s_add_i32 s37, 0, 0x222f4
	s_cmp_lg_u32 s37, -1
	v_mov_b32_e32 v0, s2
	v_mov_b32_e32 v1, s4
	s_cselect_b32 s2, s37, 0
	s_cselect_b32 s3, s3, 0
	s_waitcnt vmcnt(0) expcnt(0) lgkmcnt(0)
	ds_read_b32 v2, v0
	ds_read_b32 v0, v0 offset:4
	s_waitcnt lgkmcnt(0)
	v_cmp_eq_u32_e32 vcc, 0, v2
	s_and_saveexec_b64 s[44:45], vcc
	s_cbranch_execz .LBB0_441
	s_mov_b32 s22, 1
	s_mov_b64 s[2:3], 0
	s_branch .LBB0_431

; __device__ __forceinline__ int mk_tid(int wid_s) { int t = wid_s * 64 + (int)__builtin_amdgcn_mbcnt_hi(~0u, __builtin_amdgcn_mbcnt_lo(~0u, 0u)); asm volatile("" : "+v"(t)); return t; }
; __device__ __forceinline__ unsigned xb_ld(unsigned* p)              { return __hip_atomic_load(p, __ATOMIC_RELAXED, __HIP_MEMORY_SCOPE_AGENT); }
; __device__ __forceinline__ unsigned xb_add(unsigned* p, unsigned v) { return __hip_atomic_fetch_add(p, v, __ATOMIC_RELAXED, __HIP_MEMORY_SCOPE_AGENT); }
; __device__ __forceinline__ unsigned xb_xcc_id() { return (unsigned)__builtin_amdgcn_s_getreg((3 << 11) | 20) & 0xFu; }
; #define XB_SPIN(cond, bar) do { unsigned _sp = 0; while (cond) { \
;     if ((++_sp & 255u) == 0u) { if (xb_ld(&(bar)[XB_TMO])) break; if (_sp > XB_SPIN_CAP) { atomicAdd(&(bar)[XB_TMO], 1u); break; } } } } while (0)
; __device__ __forceinline__ void grid_barrier1(int wid_s, unsigned* bar, volatile unsigned* st) {
;     asm volatile("s_waitcnt vmcnt(0)" ::: "memory");
;     __syncthreads();
;     if (mk_tid(wid_s) == 0) {
;         const unsigned x = xb_xcc_id();
;         __builtin_amdgcn_s_waitcnt(0);
;         unsigned nloc = st[0], nx = st[1];
;         if (nloc == 0u) { xcd_barrier_complete(bar, x, nloc, nx); st[0] = nloc; st[1] = nx; }
;         const unsigned old = xb_add(&bar[XB_XSUB(x)], 1u);
;         const unsigned gen = old / nloc;
;         if (old + 1u == (gen + 1u) * nloc) {
;             __builtin_amdgcn_fence(__ATOMIC_RELEASE, "agent");
;             asm volatile("s_waitcnt vmcnt(0)" ::: "memory");
;             const unsigned og = xb_add(&bar[XB_TOP], 1u);
;             const unsigned tg = og / nx;
;             if (og + 1u == (tg + 1u) * nx) xb_add(&bar[XB_TOPGEN], 1u);
;             else XB_SPIN(xb_ld(&bar[XB_TOPGEN]) == tg, bar);
;             __builtin_amdgcn_fence(__ATOMIC_ACQUIRE, "agent");
;             xb_add(&bar[XB_XGEN(x)], 1u);
;             asm volatile("s_waitcnt vmcnt(0)" ::: "memory");
;         } else {
;             XB_SPIN(xb_ld(&bar[XB_XGEN(x)]) == gen, bar);
;             __builtin_amdgcn_fence(__ATOMIC_ACQUIRE, "agent");
;             asm volatile("s_waitcnt vmcnt(0)" ::: "memory");
;         }
;     }
;     __syncthreads();
; }
.LBB0_958:
	s_or_b64 exec, exec, s[2:3]
	v_mov_b32_e32 v0, s25
	v_add_co_u32_e32 v0, vcc, 0x2000, v0
	v_mov_b32_e32 v1, s24
	s_nop 0
	v_addc_co_u32_e32 v1, vcc, 0, v1, vcc
	s_waitcnt vmcnt(0) lgkmcnt(0)
	flat_atomic_add v[0:1], v170 offset:1024
.LBB0_959:
	s_or_b64 exec, exec, s[46:47]
	s_add_i32 s19, s19, 1
	s_cmp_lg_u32 s19, s18
	s_waitcnt lgkmcnt(0)
	s_barrier
	s_cbranch_scc0 .LBB0_474
.LBB0_960:
	s_waitcnt vmcnt(0)
	v_mov_b32_e32 v0, v169
	s_waitcnt lgkmcnt(0)
	s_barrier
	s_nop 0
	v_cmp_eq_u32_e32 vcc, 0, v0
	s_and_saveexec_b64 s[46:47], vcc
	s_cbranch_execz .LBB0_959
	s_mov_b64 s[2:3], src_shared_base
	s_getreg_b32 s2, hwreg(HW_REG_XCC_ID, 0, 4)
	s_and_b32 s33, s2, 15
	s_add_i32 s37, 0, 0x222f0
	s_cmp_lg_u32 s37, -1
	s_cselect_b32 s2, s37, 0
	s_cselect_b32 s4, s3, 0
	s_add_i32 s36, 0, 0x222f4
	s_cmp_lg_u32 s36, -1
	v_mov_b32_e32 v0, s2
	v_mov_b32_e32 v1, s4
	s_cselect_b32 s2, s36, 0
	s_cselect_b32 s3, s3, 0
	s_waitcnt vmcnt(0) expcnt(0) lgkmcnt(0)
	ds_read_b32 v2, v0
	ds_read_b32 v0, v0 offset:4
	s_waitcnt lgkmcnt(0)
	v_cmp_eq_u32_e32 vcc, 0, v2
	s_and_saveexec_b64 s[56:57], vcc
	s_cbranch_execz .LBB0_975
	s_mov_b32 s22, 1
	s_mov_b64 s[2:3], 0
	s_branch .LBB0_965

; __device__ __forceinline__ int mk_tid(int wid_s) { int t = wid_s * 64 + (int)__builtin_amdgcn_mbcnt_hi(~0u, __builtin_amdgcn_mbcnt_lo(~0u, 0u)); asm volatile("" : "+v"(t)); return t; }
; __device__ __forceinline__ unsigned xb_ld(unsigned* p)              { return __hip_atomic_load(p, __ATOMIC_RELAXED, __HIP_MEMORY_SCOPE_AGENT); }
; __device__ __forceinline__ unsigned xb_add(unsigned* p, unsigned v) { return __hip_atomic_fetch_add(p, v, __ATOMIC_RELAXED, __HIP_MEMORY_SCOPE_AGENT); }
; __device__ __forceinline__ unsigned xb_xcc_id() { return (unsigned)__builtin_amdgcn_s_getreg((3 << 11) | 20) & 0xFu; }
; #define XB_SPIN(cond, bar) do { unsigned _sp = 0; while (cond) { \
;     if ((++_sp & 255u) == 0u) { if (xb_ld(&(bar)[XB_TMO])) break; if (_sp > XB_SPIN_CAP) { atomicAdd(&(bar)[XB_TMO], 1u); break; } } } } while (0)
; __device__ __forceinline__ void grid_barrier1(int wid_s, unsigned* bar, volatile unsigned* st) {
;     asm volatile("s_waitcnt vmcnt(0)" ::: "memory");
;     __syncthreads();
;     if (mk_tid(wid_s) == 0) {
;         const unsigned x = xb_xcc_id();
;         __builtin_amdgcn_s_waitcnt(0);
;         unsigned nloc = st[0], nx = st[1];
;         if (nloc == 0u) { xcd_barrier_complete(bar, x, nloc, nx); st[0] = nloc; st[1] = nx; }
;         const unsigned old = xb_add(&bar[XB_XSUB(x)], 1u);
;         const unsigned gen = old / nloc;
;         if (old + 1u == (gen + 1u) * nloc) {
;             __builtin_amdgcn_fence(__ATOMIC_RELEASE, "agent");
;             asm volatile("s_waitcnt vmcnt(0)" ::: "memory");
;             const unsigned og = xb_add(&bar[XB_TOP], 1u);
;             const unsigned tg = og / nx;
;             if (og + 1u == (tg + 1u) * nx) xb_add(&bar[XB_TOPGEN], 1u);
;             else XB_SPIN(xb_ld(&bar[XB_TOPGEN]) == tg, bar);
;             __builtin_amdgcn_fence(__ATOMIC_ACQUIRE, "agent");
;             xb_add(&bar[XB_XGEN(x)], 1u);
;             asm volatile("s_waitcnt vmcnt(0)" ::: "memory");
;         } else {
;             XB_SPIN(xb_ld(&bar[XB_XGEN(x)]) == gen, bar);
;             __builtin_amdgcn_fence(__ATOMIC_ACQUIRE, "agent");
;             asm volatile("s_waitcnt vmcnt(0)" ::: "memory");
;         }
;     }
;     __syncthreads();
; }
.LBB0_1167:
	s_or_b64 exec, exec, s[2:3]
	v_mov_b32_e32 v0, s24
	v_add_co_u32_e32 v0, vcc, 0x2000, v0
	v_mov_b32_e32 v1, s19
	s_nop 0
	v_addc_co_u32_e32 v1, vcc, 0, v1, vcc
	s_waitcnt vmcnt(0) lgkmcnt(0)
	flat_atomic_add v[0:1], v170 offset:1024
.LBB0_1168:
	s_or_b64 exec, exec, s[44:45]
	s_add_i32 s18, s18, 1
	s_cmp_lg_u32 s18, s0
	s_waitcnt lgkmcnt(0)
	s_barrier
	s_cbranch_scc0 .LBB0_1005
.LBB0_1169:
	s_waitcnt vmcnt(0)
	v_mov_b32_e32 v0, v169
	s_waitcnt lgkmcnt(0)
	s_barrier
	s_nop 0
	v_cmp_eq_u32_e32 vcc, 0, v0
	s_and_saveexec_b64 s[44:45], vcc
	s_cbranch_execz .LBB0_1168
	s_mov_b64 s[2:3], src_shared_base
	s_getreg_b32 s2, hwreg(HW_REG_XCC_ID, 0, 4)
	s_and_b32 s19, s2, 15
	s_add_i32 s36, 0, 0x222f0
	s_cmp_lg_u32 s36, -1
	s_cselect_b32 s2, s36, 0
	s_cselect_b32 s4, s3, 0
	s_add_i32 s33, 0, 0x222f4
	s_cmp_lg_u32 s33, -1
	v_mov_b32_e32 v0, s2
	v_mov_b32_e32 v1, s4
	s_cselect_b32 s2, s33, 0
	s_cselect_b32 s3, s3, 0
	s_waitcnt vmcnt(0) expcnt(0) lgkmcnt(0)
	ds_read_b32 v2, v0
	ds_read_b32 v0, v0 offset:4
	s_waitcnt lgkmcnt(0)
	v_cmp_eq_u32_e32 vcc, 0, v2
	s_and_saveexec_b64 s[46:47], vcc
	s_cbranch_execz .LBB0_1184
	s_mov_b32 s22, 1
	s_mov_b64 s[2:3], 0
	s_branch .LBB0_1174

; __device__ __forceinline__ int mk_tid(int wid_s) { int t = wid_s * 64 + (int)__builtin_amdgcn_mbcnt_hi(~0u, __builtin_amdgcn_mbcnt_lo(~0u, 0u)); asm volatile("" : "+v"(t)); return t; }
; __device__ __forceinline__ unsigned xb_ld(unsigned* p)              { return __hip_atomic_load(p, __ATOMIC_RELAXED, __HIP_MEMORY_SCOPE_AGENT); }
; __device__ __forceinline__ unsigned xb_add(unsigned* p, unsigned v) { return __hip_atomic_fetch_add(p, v, __ATOMIC_RELAXED, __HIP_MEMORY_SCOPE_AGENT); }
; __device__ __forceinline__ unsigned xb_xcc_id() { return (unsigned)__builtin_amdgcn_s_getreg((3 << 11) | 20) & 0xFu; }
; #define XB_SPIN(cond, bar) do { unsigned _sp = 0; while (cond) { \
;     if ((++_sp & 255u) == 0u) { if (xb_ld(&(bar)[XB_TMO])) break; if (_sp > XB_SPIN_CAP) { atomicAdd(&(bar)[XB_TMO], 1u); break; } } } } while (0)
; __device__ __forceinline__ void grid_barrier1(int wid_s, unsigned* bar, volatile unsigned* st) {
;     asm volatile("s_waitcnt vmcnt(0)" ::: "memory");
;     __syncthreads();
;     if (mk_tid(wid_s) == 0) {
;         const unsigned x = xb_xcc_id();
;         __builtin_amdgcn_s_waitcnt(0);
;         unsigned nloc = st[0], nx = st[1];
;         if (nloc == 0u) { xcd_barrier_complete(bar, x, nloc, nx); st[0] = nloc; st[1] = nx; }
;         const unsigned old = xb_add(&bar[XB_XSUB(x)], 1u);
;         const unsigned gen = old / nloc;
;         if (old + 1u == (gen + 1u) * nloc) {
;             __builtin_amdgcn_fence(__ATOMIC_RELEASE, "agent");
;             asm volatile("s_waitcnt vmcnt(0)" ::: "memory");
;             const unsigned og = xb_add(&bar[XB_TOP], 1u);
;             const unsigned tg = og / nx;
;             if (og + 1u == (tg + 1u) * nx) xb_add(&bar[XB_TOPGEN], 1u);
;             else XB_SPIN(xb_ld(&bar[XB_TOPGEN]) == tg, bar);
;             __builtin_amdgcn_fence(__ATOMIC_ACQUIRE, "agent");
;             xb_add(&bar[XB_XGEN(x)], 1u);
;             asm volatile("s_waitcnt vmcnt(0)" ::: "memory");
;         } else {
;             XB_SPIN(xb_ld(&bar[XB_XGEN(x)]) == gen, bar);
;             __builtin_amdgcn_fence(__ATOMIC_ACQUIRE, "agent");
;             asm volatile("s_waitcnt vmcnt(0)" ::: "memory");
;         }
;     }
;     __syncthreads();
; }
.LBB0_1239:
	s_or_b64 exec, exec, s[2:3]
	v_mov_b32_e32 v0, s25
	v_add_co_u32_e32 v0, vcc, 0x2000, v0
	v_mov_b32_e32 v1, s24
	s_nop 0
	v_addc_co_u32_e32 v1, vcc, 0, v1, vcc
	s_waitcnt vmcnt(0) lgkmcnt(0)
	flat_atomic_add v[0:1], v170 offset:1024
.LBB0_1240:
	s_or_b64 exec, exec, s[46:47]
	s_add_i32 s36, s36, 1
	s_cmp_lg_u32 s36, s33
	s_waitcnt lgkmcnt(0)
	s_barrier
	s_cbranch_scc0 .LBB0_1214
.LBB0_1241:
	s_waitcnt vmcnt(0)
	v_mov_b32_e32 v0, v169
	s_waitcnt vmcnt(0) lgkmcnt(0)
	s_barrier
	s_nop 0
	v_cmp_eq_u32_e32 vcc, 0, v0
	s_and_saveexec_b64 s[46:47], vcc
	s_cbranch_execz .LBB0_1240
	s_mov_b64 s[2:3], src_shared_base
	s_getreg_b32 s2, hwreg(HW_REG_XCC_ID, 0, 4)
	s_and_b32 s37, s2, 15
	s_add_i32 s40, 0, 0x222f0
	s_cmp_lg_u32 s40, -1
	s_cselect_b32 s2, s40, 0
	s_cselect_b32 s4, s3, 0
	s_add_i32 s39, 0, 0x222f4
	s_cmp_lg_u32 s39, -1
	v_mov_b32_e32 v0, s2
	v_mov_b32_e32 v1, s4
	s_cselect_b32 s2, s39, 0
	s_cselect_b32 s3, s3, 0
	s_waitcnt vmcnt(0) expcnt(0) lgkmcnt(0)
	ds_read_b32 v2, v0
	ds_read_b32 v0, v0 offset:4
	s_waitcnt lgkmcnt(0)
	v_cmp_eq_u32_e32 vcc, 0, v2
	s_and_saveexec_b64 s[56:57], vcc
	s_cbranch_execz .LBB0_1256
	s_mov_b32 s22, 1
	s_mov_b64 s[2:3], 0
	s_branch .LBB0_1246

; __device__ __forceinline__ int mk_tid(int wid_s) { int t = wid_s * 64 + (int)__builtin_amdgcn_mbcnt_hi(~0u, __builtin_amdgcn_mbcnt_lo(~0u, 0u)); asm volatile("" : "+v"(t)); return t; }
; __device__ __forceinline__ unsigned xb_ld(unsigned* p)              { return __hip_atomic_load(p, __ATOMIC_RELAXED, __HIP_MEMORY_SCOPE_AGENT); }
; __device__ __forceinline__ unsigned xb_add(unsigned* p, unsigned v) { return __hip_atomic_fetch_add(p, v, __ATOMIC_RELAXED, __HIP_MEMORY_SCOPE_AGENT); }
; __device__ __forceinline__ unsigned xb_xcc_id() { return (unsigned)__builtin_amdgcn_s_getreg((3 << 11) | 20) & 0xFu; }
; #define XB_SPIN(cond, bar) do { unsigned _sp = 0; while (cond) { \
;     if ((++_sp & 255u) == 0u) { if (xb_ld(&(bar)[XB_TMO])) break; if (_sp > XB_SPIN_CAP) { atomicAdd(&(bar)[XB_TMO], 1u); break; } } } } while (0)
; __device__ __forceinline__ void grid_barrier1(int wid_s, unsigned* bar, volatile unsigned* st) {
;     asm volatile("s_waitcnt vmcnt(0)" ::: "memory");
;     __syncthreads();
;     if (mk_tid(wid_s) == 0) {
;         const unsigned x = xb_xcc_id();
;         __builtin_amdgcn_s_waitcnt(0);
;         unsigned nloc = st[0], nx = st[1];
;         if (nloc == 0u) { xcd_barrier_complete(bar, x, nloc, nx); st[0] = nloc; st[1] = nx; }
;         const unsigned old = xb_add(&bar[XB_XSUB(x)], 1u);
;         const unsigned gen = old / nloc;
;         if (old + 1u == (gen + 1u) * nloc) {
;             __builtin_amdgcn_fence(__ATOMIC_RELEASE, "agent");
;             asm volatile("s_waitcnt vmcnt(0)" ::: "memory");
;             const unsigned og = xb_add(&bar[XB_TOP], 1u);
;             const unsigned tg = og / nx;
;             if (og + 1u == (tg + 1u) * nx) xb_add(&bar[XB_TOPGEN], 1u);
;             else XB_SPIN(xb_ld(&bar[XB_TOPGEN]) == tg, bar);
;             __builtin_amdgcn_fence(__ATOMIC_ACQUIRE, "agent");
;             xb_add(&bar[XB_XGEN(x)], 1u);
;             asm volatile("s_waitcnt vmcnt(0)" ::: "memory");
;         } else {
;             XB_SPIN(xb_ld(&bar[XB_XGEN(x)]) == gen, bar);
;             __builtin_amdgcn_fence(__ATOMIC_ACQUIRE, "agent");
;             asm volatile("s_waitcnt vmcnt(0)" ::: "memory");
;         }
;     }
;     __syncthreads();
; }
.LBB0_1301:
	s_or_b64 exec, exec, s[2:3]
	v_mov_b32_e32 v0, s24
	v_add_co_u32_e32 v0, vcc, 0x2000, v0
	v_mov_b32_e32 v1, s19
	s_nop 0
	v_addc_co_u32_e32 v1, vcc, 0, v1, vcc
	s_waitcnt vmcnt(0) lgkmcnt(0)
	flat_atomic_add v[0:1], v170 offset:1024
.LBB0_1302:
	s_or_b64 exec, exec, s[44:45]
	s_add_i32 s18, s18, 1
	s_cmp_lg_u32 s18, s0
	s_waitcnt lgkmcnt(0)
	s_barrier
	s_cbranch_scc0 .LBB0_1346
.LBB0_1303:
	s_waitcnt vmcnt(0)
	v_mov_b32_e32 v0, v169
	s_waitcnt vmcnt(0)
	s_barrier
	s_nop 0
	v_cmp_eq_u32_e32 vcc, 0, v0
	s_and_saveexec_b64 s[44:45], vcc
	s_cbranch_execz .LBB0_1302
	s_mov_b64 s[2:3], src_shared_base
	s_getreg_b32 s2, hwreg(HW_REG_XCC_ID, 0, 4)
	s_and_b32 s19, s2, 15
	s_add_i32 s36, 0, 0x222f0
	s_cmp_lg_u32 s36, -1
	s_cselect_b32 s2, s36, 0
	s_cselect_b32 s4, s3, 0
	s_add_i32 s33, 0, 0x222f4
	s_cmp_lg_u32 s33, -1
	v_mov_b32_e32 v0, s2
	v_mov_b32_e32 v1, s4
	s_cselect_b32 s2, s33, 0
	s_cselect_b32 s3, s3, 0
	s_waitcnt vmcnt(0) expcnt(0) lgkmcnt(0)
	ds_read_b32 v2, v0
	ds_read_b32 v0, v0 offset:4
	s_waitcnt lgkmcnt(0)
	v_cmp_eq_u32_e32 vcc, 0, v2
	s_and_saveexec_b64 s[46:47], vcc
	s_cbranch_execz .LBB0_1318
	s_mov_b32 s22, 1
	s_mov_b64 s[2:3], 0
	s_branch .LBB0_1308

; __device__ __forceinline__ int mk_tid(int wid_s) { int t = wid_s * 64 + (int)__builtin_amdgcn_mbcnt_hi(~0u, __builtin_amdgcn_mbcnt_lo(~0u, 0u)); asm volatile("" : "+v"(t)); return t; }
; __device__ __forceinline__ unsigned xb_ld(unsigned* p)              { return __hip_atomic_load(p, __ATOMIC_RELAXED, __HIP_MEMORY_SCOPE_AGENT); }
; __device__ __forceinline__ unsigned xb_add(unsigned* p, unsigned v) { return __hip_atomic_fetch_add(p, v, __ATOMIC_RELAXED, __HIP_MEMORY_SCOPE_AGENT); }
; __device__ __forceinline__ unsigned xb_xcc_id() { return (unsigned)__builtin_amdgcn_s_getreg((3 << 11) | 20) & 0xFu; }
; #define XB_SPIN(cond, bar) do { unsigned _sp = 0; while (cond) { \
;     if ((++_sp & 255u) == 0u) { if (xb_ld(&(bar)[XB_TMO])) break; if (_sp > XB_SPIN_CAP) { atomicAdd(&(bar)[XB_TMO], 1u); break; } } } } while (0)
; __device__ __forceinline__ void grid_barrier1(int wid_s, unsigned* bar, volatile unsigned* st) {
;     asm volatile("s_waitcnt vmcnt(0)" ::: "memory");
;     __syncthreads();
;     if (mk_tid(wid_s) == 0) {
;         const unsigned x = xb_xcc_id();
;         __builtin_amdgcn_s_waitcnt(0);
;         unsigned nloc = st[0], nx = st[1];
;         if (nloc == 0u) { xcd_barrier_complete(bar, x, nloc, nx); st[0] = nloc; st[1] = nx; }
;         const unsigned old = xb_add(&bar[XB_XSUB(x)], 1u);
;         const unsigned gen = old / nloc;
;         if (old + 1u == (gen + 1u) * nloc) {
;             __builtin_amdgcn_fence(__ATOMIC_RELEASE, "agent");
;             asm volatile("s_waitcnt vmcnt(0)" ::: "memory");
;             const unsigned og = xb_add(&bar[XB_TOP], 1u);
;             const unsigned tg = og / nx;
;             if (og + 1u == (tg + 1u) * nx) xb_add(&bar[XB_TOPGEN], 1u);
;             else XB_SPIN(xb_ld(&bar[XB_TOPGEN]) == tg, bar);
;             __builtin_amdgcn_fence(__ATOMIC_ACQUIRE, "agent");
;             xb_add(&bar[XB_XGEN(x)], 1u);
;             asm volatile("s_waitcnt vmcnt(0)" ::: "memory");
;         } else {
;             XB_SPIN(xb_ld(&bar[XB_XGEN(x)]) == gen, bar);
;             __builtin_amdgcn_fence(__ATOMIC_ACQUIRE, "agent");
;             asm volatile("s_waitcnt vmcnt(0)" ::: "memory");
;         }
;     }
;     __syncthreads();
; }
.LBB0_1452:
	s_or_b64 exec, exec, s[2:3]
	v_mov_b32_e32 v0, s24
	v_add_co_u32_e32 v0, vcc, 0x2000, v0
	v_mov_b32_e32 v1, s19
	s_nop 0
	v_addc_co_u32_e32 v1, vcc, 0, v1, vcc
	s_waitcnt vmcnt(0) lgkmcnt(0)
	flat_atomic_add v[0:1], v170 offset:1024
.LBB0_1453:
	s_or_b64 exec, exec, s[44:45]
	s_add_i32 s18, s18, 1
	s_cmp_lg_u32 s18, s0
	s_waitcnt lgkmcnt(0)
	s_barrier
	s_cbranch_scc0 .LBB0_1348
.LBB0_1454:
	s_waitcnt vmcnt(0)
	v_mov_b32_e32 v0, v169
	s_barrier
	s_nop 0
	v_cmp_eq_u32_e32 vcc, 0, v0
	s_and_saveexec_b64 s[44:45], vcc
	s_cbranch_execz .LBB0_1453
	s_mov_b64 s[2:3], src_shared_base
	s_getreg_b32 s2, hwreg(HW_REG_XCC_ID, 0, 4)
	s_and_b32 s19, s2, 15
	s_add_i32 s36, 0, 0x222f0
	s_cmp_lg_u32 s36, -1
	s_cselect_b32 s2, s36, 0
	s_cselect_b32 s4, s3, 0
	s_add_i32 s33, 0, 0x222f4
	s_cmp_lg_u32 s33, -1
	v_mov_b32_e32 v0, s2
	v_mov_b32_e32 v1, s4
	s_cselect_b32 s2, s33, 0
	s_cselect_b32 s3, s3, 0
	s_waitcnt vmcnt(0) expcnt(0) lgkmcnt(0)
	ds_read_b32 v2, v0
	ds_read_b32 v0, v0 offset:4
	s_waitcnt lgkmcnt(0)
	v_cmp_eq_u32_e32 vcc, 0, v2
	s_and_saveexec_b64 s[46:47], vcc
	s_cbranch_execz .LBB0_1469
	s_mov_b32 s22, 1
	s_mov_b64 s[2:3], 0
	s_branch .LBB0_1459

; __device__ __forceinline__ unsigned xb_ld(unsigned* p)              { return __hip_atomic_load(p, __ATOMIC_RELAXED, __HIP_MEMORY_SCOPE_AGENT); }
; __device__ __forceinline__ unsigned xb_add(unsigned* p, unsigned v) { return __hip_atomic_fetch_add(p, v, __ATOMIC_RELAXED, __HIP_MEMORY_SCOPE_AGENT); }
; #define XB_SPIN(cond, bar) do { unsigned _sp = 0; while (cond) { \
;     if ((++_sp & 255u) == 0u) { if (xb_ld(&(bar)[XB_TMO])) break; if (_sp > XB_SPIN_CAP) { atomicAdd(&(bar)[XB_TMO], 1u); break; } } } } while (0)
; __device__ __forceinline__ void grid_barrier1(int wid_s, unsigned* bar, volatile unsigned* st) {
;     ...
;             xb_add(&bar[XB_XGEN(x)], 1u);
;             asm volatile("s_waitcnt vmcnt(0)" ::: "memory");
;         } else {
;             XB_SPIN(xb_ld(&bar[XB_XGEN(x)]) == gen, bar);
;             __builtin_amdgcn_fence(__ATOMIC_ACQUIRE, "agent");
;             asm volatile("s_waitcnt vmcnt(0)" ::: "memory");
;         }
;     }
;     __syncthreads();
; }
.LBB0_1505:
	s_or_b64 exec, exec, s[2:3]
	v_mov_b32_e32 v0, s24
	v_add_co_u32_e32 v0, vcc, 0x2000, v0
	v_mov_b32_e32 v1, s19
	s_nop 0
	v_addc_co_u32_e32 v1, vcc, 0, v1, vcc
	s_waitcnt vmcnt(0) lgkmcnt(0)
	flat_atomic_add v[0:1], v170 offset:1024
.LBB0_1506:
	s_or_b64 exec, exec, s[44:45]
	s_add_i32 s18, s18, 1
	s_cmp_lg_u32 s18, s0
	s_waitcnt lgkmcnt(0)
	s_barrier
	s_cbranch_scc0 .LBB0_471

; __device__ __forceinline__ int mk_tid(int wid_s) { int t = wid_s * 64 + (int)__builtin_amdgcn_mbcnt_hi(~0u, __builtin_amdgcn_mbcnt_lo(~0u, 0u)); asm volatile("" : "+v"(t)); return t; }
; __device__ __forceinline__ unsigned xb_ld(unsigned* p)              { return __hip_atomic_load(p, __ATOMIC_RELAXED, __HIP_MEMORY_SCOPE_AGENT); }
; __device__ __forceinline__ unsigned xb_add(unsigned* p, unsigned v) { return __hip_atomic_fetch_add(p, v, __ATOMIC_RELAXED, __HIP_MEMORY_SCOPE_AGENT); }
; __device__ __forceinline__ unsigned xb_xcc_id() { return (unsigned)__builtin_amdgcn_s_getreg((3 << 11) | 20) & 0xFu; }
; #define XB_SPIN(cond, bar) do { unsigned _sp = 0; while (cond) { \
;     if ((++_sp & 255u) == 0u) { if (xb_ld(&(bar)[XB_TMO])) break; if (_sp > XB_SPIN_CAP) { atomicAdd(&(bar)[XB_TMO], 1u); break; } } } } while (0)
; __device__ __forceinline__ void grid_barrier1(int wid_s, unsigned* bar, volatile unsigned* st) {
;     asm volatile("s_waitcnt vmcnt(0)" ::: "memory");
;     __syncthreads();
;     if (mk_tid(wid_s) == 0) {
;         const unsigned x = xb_xcc_id();
;         __builtin_amdgcn_s_waitcnt(0);
;         unsigned nloc = st[0], nx = st[1];
;         if (nloc == 0u) { xcd_barrier_complete(bar, x, nloc, nx); st[0] = nloc; st[1] = nx; }
;         const unsigned old = xb_add(&bar[XB_XSUB(x)], 1u);
;         const unsigned gen = old / nloc;
;         if (old + 1u == (gen + 1u) * nloc) {
;             __builtin_amdgcn_fence(__ATOMIC_RELEASE, "agent");
;             asm volatile("s_waitcnt vmcnt(0)" ::: "memory");
;             const unsigned og = xb_add(&bar[XB_TOP], 1u);
;             const unsigned tg = og / nx;
;             if (og + 1u == (tg + 1u) * nx) xb_add(&bar[XB_TOPGEN], 1u);
;             else XB_SPIN(xb_ld(&bar[XB_TOPGEN]) == tg, bar);
;             __builtin_amdgcn_fence(__ATOMIC_ACQUIRE, "agent");
;             xb_add(&bar[XB_XGEN(x)], 1u);
;             asm volatile("s_waitcnt vmcnt(0)" ::: "memory");
;         } else {
;             XB_SPIN(xb_ld(&bar[XB_XGEN(x)]) == gen, bar);
;             __builtin_amdgcn_fence(__ATOMIC_ACQUIRE, "agent");
;             asm volatile("s_waitcnt vmcnt(0)" ::: "memory");
;         }
;     }
;     __syncthreads();
; }
.LBB0_1644:
	s_or_b64 exec, exec, s[2:3]
	v_mov_b32_e32 v0, s24
	v_add_co_u32_e32 v0, vcc, 0x2000, v0
	v_mov_b32_e32 v1, s19
	s_nop 0
	v_addc_co_u32_e32 v1, vcc, 0, v1, vcc
	s_waitcnt vmcnt(0) lgkmcnt(0)
	flat_atomic_add v[0:1], v170 offset:1024
.LBB0_1645:
	s_or_b64 exec, exec, s[46:47]
	s_add_i32 s18, s18, 1
	s_cmp_lg_u32 s18, s0
	s_waitcnt lgkmcnt(0)
	s_barrier
	s_cbranch_scc0 .LBB0_1555
.LBB0_1646:
	s_waitcnt vmcnt(0)
	v_mov_b32_e32 v0, v169
	s_waitcnt vmcnt(0) lgkmcnt(0)
	s_barrier
	s_nop 0
	v_cmp_eq_u32_e32 vcc, 0, v0
	s_and_saveexec_b64 s[46:47], vcc
	s_cbranch_execz .LBB0_1645
	s_mov_b64 s[2:3], src_shared_base
	s_getreg_b32 s2, hwreg(HW_REG_XCC_ID, 0, 4)
	s_and_b32 s19, s2, 15
	s_add_i32 s36, 0, 0x222f0
	s_cmp_lg_u32 s36, -1
	s_cselect_b32 s2, s36, 0
	s_cselect_b32 s4, s3, 0
	s_add_i32 s33, 0, 0x222f4
	s_cmp_lg_u32 s33, -1
	v_mov_b32_e32 v0, s2
	v_mov_b32_e32 v1, s4
	s_cselect_b32 s2, s33, 0
	s_cselect_b32 s3, s3, 0
	s_waitcnt vmcnt(0) expcnt(0) lgkmcnt(0)
	ds_read_b32 v2, v0
	ds_read_b32 v0, v0 offset:4
	s_waitcnt lgkmcnt(0)
	v_cmp_eq_u32_e32 vcc, 0, v2
	s_and_saveexec_b64 s[52:53], vcc
	s_cbranch_execz .LBB0_1661
	s_mov_b32 s22, 1
	s_mov_b64 s[2:3], 0
	s_branch .LBB0_1651

; __device__ __forceinline__ int mk_tid(int wid_s) { int t = wid_s * 64 + (int)__builtin_amdgcn_mbcnt_hi(~0u, __builtin_amdgcn_mbcnt_lo(~0u, 0u)); asm volatile("" : "+v"(t)); return t; }
; __device__ __forceinline__ unsigned xb_ld(unsigned* p)              { return __hip_atomic_load(p, __ATOMIC_RELAXED, __HIP_MEMORY_SCOPE_AGENT); }
; __device__ __forceinline__ unsigned xb_add(unsigned* p, unsigned v) { return __hip_atomic_fetch_add(p, v, __ATOMIC_RELAXED, __HIP_MEMORY_SCOPE_AGENT); }
; __device__ __forceinline__ unsigned xb_xcc_id() { return (unsigned)__builtin_amdgcn_s_getreg((3 << 11) | 20) & 0xFu; }
; #define XB_SPIN(cond, bar) do { unsigned _sp = 0; while (cond) { \
;     if ((++_sp & 255u) == 0u) { if (xb_ld(&(bar)[XB_TMO])) break; if (_sp > XB_SPIN_CAP) { atomicAdd(&(bar)[XB_TMO], 1u); break; } } } } while (0)
; __device__ __forceinline__ void grid_barrier1(int wid_s, unsigned* bar, volatile unsigned* st) {
;     asm volatile("s_waitcnt vmcnt(0)" ::: "memory");
;     __syncthreads();
;     if (mk_tid(wid_s) == 0) {
;         const unsigned x = xb_xcc_id();
;         __builtin_amdgcn_s_waitcnt(0);
;         unsigned nloc = st[0], nx = st[1];
;         if (nloc == 0u) { xcd_barrier_complete(bar, x, nloc, nx); st[0] = nloc; st[1] = nx; }
;         const unsigned old = xb_add(&bar[XB_XSUB(x)], 1u);
;         const unsigned gen = old / nloc;
;         if (old + 1u == (gen + 1u) * nloc) {
;             __builtin_amdgcn_fence(__ATOMIC_RELEASE, "agent");
;             asm volatile("s_waitcnt vmcnt(0)" ::: "memory");
;             const unsigned og = xb_add(&bar[XB_TOP], 1u);
;             const unsigned tg = og / nx;
;             if (og + 1u == (tg + 1u) * nx) xb_add(&bar[XB_TOPGEN], 1u);
;             else XB_SPIN(xb_ld(&bar[XB_TOPGEN]) == tg, bar);
;             __builtin_amdgcn_fence(__ATOMIC_ACQUIRE, "agent");
;             xb_add(&bar[XB_XGEN(x)], 1u);
;             asm volatile("s_waitcnt vmcnt(0)" ::: "memory");
;         } else {
;             XB_SPIN(xb_ld(&bar[XB_XGEN(x)]) == gen, bar);
;             __builtin_amdgcn_fence(__ATOMIC_ACQUIRE, "agent");
;             asm volatile("s_waitcnt vmcnt(0)" ::: "memory");
;         }
;     }
;     __syncthreads();
; }
.LBB0_1776:
	s_or_b64 exec, exec, s[2:3]
	v_mov_b32_e32 v0, s25
	v_add_co_u32_e32 v0, vcc, 0x2000, v0
	v_mov_b32_e32 v1, s24
	s_nop 0
	v_addc_co_u32_e32 v1, vcc, 0, v1, vcc
	s_waitcnt vmcnt(0) lgkmcnt(0)
	flat_atomic_add v[0:1], v170 offset:1024
.LBB0_1777:
	s_or_b64 exec, exec, s[44:45]
	s_add_i32 s33, s33, 1
	s_cmp_lg_u32 s33, s0
	s_waitcnt lgkmcnt(0)
	s_barrier
	s_cbranch_scc0 .LBB0_1691
.LBB0_1778:
	s_waitcnt vmcnt(0)
	v_mov_b32_e32 v0, v169
	s_waitcnt vmcnt(0) lgkmcnt(0)
	s_barrier
	s_nop 0
	v_cmp_eq_u32_e32 vcc, 0, v0
	s_and_saveexec_b64 s[44:45], vcc
	s_cbranch_execz .LBB0_1777
	s_mov_b64 s[2:3], src_shared_base
	s_getreg_b32 s2, hwreg(HW_REG_XCC_ID, 0, 4)
	s_and_b32 s36, s2, 15
	s_add_i32 s39, 0, 0x222f0
	s_cmp_lg_u32 s39, -1
	s_cselect_b32 s2, s39, 0
	s_cselect_b32 s4, s3, 0
	s_add_i32 s37, 0, 0x222f4
	s_cmp_lg_u32 s37, -1
	v_mov_b32_e32 v0, s2
	v_mov_b32_e32 v1, s4
	s_cselect_b32 s2, s37, 0
	s_cselect_b32 s3, s3, 0
	s_waitcnt vmcnt(0) expcnt(0) lgkmcnt(0)
	ds_read_b32 v2, v0
	ds_read_b32 v0, v0 offset:4
	s_waitcnt lgkmcnt(0)
	v_cmp_eq_u32_e32 vcc, 0, v2
	s_and_saveexec_b64 s[46:47], vcc
	s_cbranch_execz .LBB0_1793
	s_mov_b32 s22, 1
	s_mov_b64 s[2:3], 0
	s_branch .LBB0_1783

; __device__ __forceinline__ int mk_tid(int wid_s) { int t = wid_s * 64 + (int)__builtin_amdgcn_mbcnt_hi(~0u, __builtin_amdgcn_mbcnt_lo(~0u, 0u)); asm volatile("" : "+v"(t)); return t; }
; __device__ __forceinline__ unsigned xb_ld(unsigned* p)              { return __hip_atomic_load(p, __ATOMIC_RELAXED, __HIP_MEMORY_SCOPE_AGENT); }
; __device__ __forceinline__ unsigned xb_add(unsigned* p, unsigned v) { return __hip_atomic_fetch_add(p, v, __ATOMIC_RELAXED, __HIP_MEMORY_SCOPE_AGENT); }
; __device__ __forceinline__ unsigned xb_xcc_id() { return (unsigned)__builtin_amdgcn_s_getreg((3 << 11) | 20) & 0xFu; }
; #define XB_SPIN(cond, bar) do { unsigned _sp = 0; while (cond) { \
;     if ((++_sp & 255u) == 0u) { if (xb_ld(&(bar)[XB_TMO])) break; if (_sp > XB_SPIN_CAP) { atomicAdd(&(bar)[XB_TMO], 1u); break; } } } } while (0)
; __device__ __forceinline__ void grid_barrier1(int wid_s, unsigned* bar, volatile unsigned* st) {
;     asm volatile("s_waitcnt vmcnt(0)" ::: "memory");
;     __syncthreads();
;     if (mk_tid(wid_s) == 0) {
;         const unsigned x = xb_xcc_id();
;         __builtin_amdgcn_s_waitcnt(0);
;         unsigned nloc = st[0], nx = st[1];
;         if (nloc == 0u) { xcd_barrier_complete(bar, x, nloc, nx); st[0] = nloc; st[1] = nx; }
;         const unsigned old = xb_add(&bar[XB_XSUB(x)], 1u);
;         const unsigned gen = old / nloc;
;         if (old + 1u == (gen + 1u) * nloc) {
;             __builtin_amdgcn_fence(__ATOMIC_RELEASE, "agent");
;             asm volatile("s_waitcnt vmcnt(0)" ::: "memory");
;             const unsigned og = xb_add(&bar[XB_TOP], 1u);
;             const unsigned tg = og / nx;
;             if (og + 1u == (tg + 1u) * nx) xb_add(&bar[XB_TOPGEN], 1u);
;             else XB_SPIN(xb_ld(&bar[XB_TOPGEN]) == tg, bar);
;             __builtin_amdgcn_fence(__ATOMIC_ACQUIRE, "agent");
;             xb_add(&bar[XB_XGEN(x)], 1u);
;             asm volatile("s_waitcnt vmcnt(0)" ::: "memory");
;         } else {
;             XB_SPIN(xb_ld(&bar[XB_XGEN(x)]) == gen, bar);
;             __builtin_amdgcn_fence(__ATOMIC_ACQUIRE, "agent");
;             asm volatile("s_waitcnt vmcnt(0)" ::: "memory");
;         }
;     }
;     __syncthreads();
; }
.LBB0_1856:
	s_or_b64 exec, exec, s[2:3]
	v_mov_b32_e32 v0, s24
	v_add_co_u32_e32 v0, vcc, 0x2000, v0
	v_mov_b32_e32 v1, s19
	s_nop 0
	v_addc_co_u32_e32 v1, vcc, 0, v1, vcc
	s_waitcnt vmcnt(0) lgkmcnt(0)
	flat_atomic_add v[0:1], v170 offset:1024
.LBB0_1857:
	s_or_b64 exec, exec, s[44:45]
	s_add_i32 s18, s18, 1
	s_cmp_lg_u32 s18, s0
	s_waitcnt lgkmcnt(0)
	s_barrier
	s_cbranch_scc0 .LBB0_1901
.LBB0_1858:
	s_waitcnt vmcnt(0)
	v_mov_b32_e32 v0, v169
	s_waitcnt vmcnt(0) lgkmcnt(0)
	s_barrier
	s_nop 0
	v_cmp_eq_u32_e32 vcc, 0, v0
	s_and_saveexec_b64 s[44:45], vcc
	s_cbranch_execz .LBB0_1857
	s_mov_b64 s[2:3], src_shared_base
	s_getreg_b32 s2, hwreg(HW_REG_XCC_ID, 0, 4)
	s_and_b32 s19, s2, 15
	s_add_i32 s36, 0, 0x222f0
	s_cmp_lg_u32 s36, -1
	s_cselect_b32 s2, s36, 0
	s_cselect_b32 s4, s3, 0
	s_add_i32 s33, 0, 0x222f4
	s_cmp_lg_u32 s33, -1
	v_mov_b32_e32 v0, s2
	v_mov_b32_e32 v1, s4
	s_cselect_b32 s2, s33, 0
	s_cselect_b32 s3, s3, 0
	s_waitcnt vmcnt(0) expcnt(0) lgkmcnt(0)
	ds_read_b32 v2, v0
	ds_read_b32 v0, v0 offset:4
	s_waitcnt lgkmcnt(0)
	v_cmp_eq_u32_e32 vcc, 0, v2
	s_and_saveexec_b64 s[46:47], vcc
	s_cbranch_execz .LBB0_1873
	s_mov_b32 s22, 1
	s_mov_b64 s[2:3], 0
	s_branch .LBB0_1863

; __device__ __forceinline__ int mk_tid(int wid_s) { int t = wid_s * 64 + (int)__builtin_amdgcn_mbcnt_hi(~0u, __builtin_amdgcn_mbcnt_lo(~0u, 0u)); asm volatile("" : "+v"(t)); return t; }
; __device__ __forceinline__ unsigned xb_ld(unsigned* p)              { return __hip_atomic_load(p, __ATOMIC_RELAXED, __HIP_MEMORY_SCOPE_AGENT); }
; __device__ __forceinline__ unsigned xb_add(unsigned* p, unsigned v) { return __hip_atomic_fetch_add(p, v, __ATOMIC_RELAXED, __HIP_MEMORY_SCOPE_AGENT); }
; __device__ __forceinline__ unsigned xb_xcc_id() { return (unsigned)__builtin_amdgcn_s_getreg((3 << 11) | 20) & 0xFu; }
; #define XB_SPIN(cond, bar) do { unsigned _sp = 0; while (cond) { \
;     if ((++_sp & 255u) == 0u) { if (xb_ld(&(bar)[XB_TMO])) break; if (_sp > XB_SPIN_CAP) { atomicAdd(&(bar)[XB_TMO], 1u); break; } } } } while (0)
; __device__ __forceinline__ void grid_barrier1(int wid_s, unsigned* bar, volatile unsigned* st) {
;     asm volatile("s_waitcnt vmcnt(0)" ::: "memory");
;     __syncthreads();
;     if (mk_tid(wid_s) == 0) {
;         const unsigned x = xb_xcc_id();
;         __builtin_amdgcn_s_waitcnt(0);
;         unsigned nloc = st[0], nx = st[1];
;         if (nloc == 0u) { xcd_barrier_complete(bar, x, nloc, nx); st[0] = nloc; st[1] = nx; }
;         const unsigned old = xb_add(&bar[XB_XSUB(x)], 1u);
;         const unsigned gen = old / nloc;
;         if (old + 1u == (gen + 1u) * nloc) {
;             __builtin_amdgcn_fence(__ATOMIC_RELEASE, "agent");
;             asm volatile("s_waitcnt vmcnt(0)" ::: "memory");
;             const unsigned og = xb_add(&bar[XB_TOP], 1u);
;             const unsigned tg = og / nx;
;             if (og + 1u == (tg + 1u) * nx) xb_add(&bar[XB_TOPGEN], 1u);
;             else XB_SPIN(xb_ld(&bar[XB_TOPGEN]) == tg, bar);
;             __builtin_amdgcn_fence(__ATOMIC_ACQUIRE, "agent");
;             xb_add(&bar[XB_XGEN(x)], 1u);
;             asm volatile("s_waitcnt vmcnt(0)" ::: "memory");
;         } else {
;             XB_SPIN(xb_ld(&bar[XB_XGEN(x)]) == gen, bar);
;             __builtin_amdgcn_fence(__ATOMIC_ACQUIRE, "agent");
;             asm volatile("s_waitcnt vmcnt(0)" ::: "memory");
;         }
;     }
;     __syncthreads();
; }
.LBB0_2158:
	s_or_b64 exec, exec, s[2:3]
	v_mov_b32_e32 v0, s25
	v_add_co_u32_e32 v0, vcc, 0x2000, v0
	v_mov_b32_e32 v1, s24
	s_nop 0
	v_addc_co_u32_e32 v1, vcc, 0, v1, vcc
	s_waitcnt vmcnt(0) lgkmcnt(0)
	flat_atomic_add v[0:1], v170 offset:1024
.LBB0_2159:
	s_or_b64 exec, exec, s[44:45]
	s_add_i32 s36, s36, 1
	s_cmp_lg_u32 s36, s33
	s_waitcnt lgkmcnt(0)
	s_barrier
	s_cbranch_scc0 .LBB0_2125
.LBB0_2160:
	s_waitcnt vmcnt(0)
	v_mov_b32_e32 v0, v169
	s_waitcnt vmcnt(0) lgkmcnt(0)
	s_barrier
	s_nop 0
	v_cmp_eq_u32_e32 vcc, 0, v0
	s_and_saveexec_b64 s[44:45], vcc
	s_cbranch_execz .LBB0_2159
	s_mov_b64 s[2:3], src_shared_base
	s_getreg_b32 s2, hwreg(HW_REG_XCC_ID, 0, 4)
	s_and_b32 s37, s2, 15
	s_add_i32 s40, 0, 0x222f0
	s_cmp_lg_u32 s40, -1
	s_cselect_b32 s2, s40, 0
	s_cselect_b32 s4, s3, 0
	s_add_i32 s39, 0, 0x222f4
	s_cmp_lg_u32 s39, -1
	v_mov_b32_e32 v0, s2
	v_mov_b32_e32 v1, s4
	s_cselect_b32 s2, s39, 0
	s_cselect_b32 s3, s3, 0
	s_waitcnt vmcnt(0) expcnt(0) lgkmcnt(0)
	ds_read_b32 v2, v0
	ds_read_b32 v0, v0 offset:4
	s_waitcnt lgkmcnt(0)
	v_cmp_eq_u32_e32 vcc, 0, v2
	s_and_saveexec_b64 s[46:47], vcc
	s_cbranch_execz .LBB0_2175
	s_mov_b32 s22, 1
	s_mov_b64 s[2:3], 0
	s_branch .LBB0_2165

; __device__ __forceinline__ int mk_tid(int wid_s) { int t = wid_s * 64 + (int)__builtin_amdgcn_mbcnt_hi(~0u, __builtin_amdgcn_mbcnt_lo(~0u, 0u)); asm volatile("" : "+v"(t)); return t; }
; __device__ __forceinline__ unsigned xb_ld(unsigned* p)              { return __hip_atomic_load(p, __ATOMIC_RELAXED, __HIP_MEMORY_SCOPE_AGENT); }
; __device__ __forceinline__ unsigned xb_add(unsigned* p, unsigned v) { return __hip_atomic_fetch_add(p, v, __ATOMIC_RELAXED, __HIP_MEMORY_SCOPE_AGENT); }
; __device__ __forceinline__ unsigned xb_xcc_id() { return (unsigned)__builtin_amdgcn_s_getreg((3 << 11) | 20) & 0xFu; }
; #define XB_SPIN(cond, bar) do { unsigned _sp = 0; while (cond) { \
;     if ((++_sp & 255u) == 0u) { if (xb_ld(&(bar)[XB_TMO])) break; if (_sp > XB_SPIN_CAP) { atomicAdd(&(bar)[XB_TMO], 1u); break; } } } } while (0)
; __device__ __forceinline__ void grid_barrier1(int wid_s, unsigned* bar, volatile unsigned* st) {
;     asm volatile("s_waitcnt vmcnt(0)" ::: "memory");
;     __syncthreads();
;     if (mk_tid(wid_s) == 0) {
;         const unsigned x = xb_xcc_id();
;         __builtin_amdgcn_s_waitcnt(0);
;         unsigned nloc = st[0], nx = st[1];
;         if (nloc == 0u) { xcd_barrier_complete(bar, x, nloc, nx); st[0] = nloc; st[1] = nx; }
;         const unsigned old = xb_add(&bar[XB_XSUB(x)], 1u);
;         const unsigned gen = old / nloc;
;         if (old + 1u == (gen + 1u) * nloc) {
;             __builtin_amdgcn_fence(__ATOMIC_RELEASE, "agent");
;             asm volatile("s_waitcnt vmcnt(0)" ::: "memory");
;             const unsigned og = xb_add(&bar[XB_TOP], 1u);
;             const unsigned tg = og / nx;
;             if (og + 1u == (tg + 1u) * nx) xb_add(&bar[XB_TOPGEN], 1u);
;             else XB_SPIN(xb_ld(&bar[XB_TOPGEN]) == tg, bar);
;             __builtin_amdgcn_fence(__ATOMIC_ACQUIRE, "agent");
;             xb_add(&bar[XB_XGEN(x)], 1u);
;             asm volatile("s_waitcnt vmcnt(0)" ::: "memory");
;         } else {
;             XB_SPIN(xb_ld(&bar[XB_XGEN(x)]) == gen, bar);
;             __builtin_amdgcn_fence(__ATOMIC_ACQUIRE, "agent");
;             asm volatile("s_waitcnt vmcnt(0)" ::: "memory");
;         }
;     }
;     __syncthreads();
; }
.LBB0_2232:
	s_or_b64 exec, exec, s[2:3]
	v_mov_b32_e32 v0, s25
	v_add_co_u32_e32 v0, vcc, 0x2000, v0
	v_mov_b32_e32 v1, s24
	s_nop 0
	v_addc_co_u32_e32 v1, vcc, 0, v1, vcc
	s_waitcnt vmcnt(0) lgkmcnt(0)
	flat_atomic_add v[0:1], v170 offset:1024
.LBB0_2233:
	s_or_b64 exec, exec, s[52:53]
	s_add_i32 s33, s33, 1
	s_cmp_lg_u32 s33, s19
	s_waitcnt lgkmcnt(0)
	s_barrier
	s_cbranch_scc0 .LBB0_2205
.LBB0_2234:
	s_waitcnt vmcnt(0)
	v_mov_b32_e32 v0, v169
	s_waitcnt vmcnt(0) lgkmcnt(0)
	s_barrier
	s_nop 0
	v_cmp_eq_u32_e32 vcc, 0, v0
	s_and_saveexec_b64 s[52:53], vcc
	s_cbranch_execz .LBB0_2233
	s_mov_b64 s[2:3], src_shared_base
	s_getreg_b32 s2, hwreg(HW_REG_XCC_ID, 0, 4)
	s_and_b32 s36, s2, 15
	s_add_i32 s39, 0, 0x222f0
	s_cmp_lg_u32 s39, -1
	s_cselect_b32 s2, s39, 0
	s_cselect_b32 s4, s3, 0
	s_add_i32 s37, 0, 0x222f4
	s_cmp_lg_u32 s37, -1
	v_mov_b32_e32 v0, s2
	v_mov_b32_e32 v1, s4
	s_cselect_b32 s2, s37, 0
	s_cselect_b32 s3, s3, 0
	s_waitcnt vmcnt(0) expcnt(0) lgkmcnt(0)
	ds_read_b32 v2, v0
	ds_read_b32 v0, v0 offset:4
	s_waitcnt lgkmcnt(0)
	v_cmp_eq_u32_e32 vcc, 0, v2
	s_and_saveexec_b64 s[46:47], vcc
	s_cbranch_execz .LBB0_2249
	s_mov_b32 s22, 1
	s_mov_b64 s[2:3], 0
	s_branch .LBB0_2239

; __device__ __forceinline__ unsigned xb_ld(unsigned* p)              { return __hip_atomic_load(p, __ATOMIC_RELAXED, __HIP_MEMORY_SCOPE_AGENT); }
; __device__ __forceinline__ unsigned xb_add(unsigned* p, unsigned v) { return __hip_atomic_fetch_add(p, v, __ATOMIC_RELAXED, __HIP_MEMORY_SCOPE_AGENT); }
; #define XB_SPIN(cond, bar) do { unsigned _sp = 0; while (cond) { \
;     if ((++_sp & 255u) == 0u) { if (xb_ld(&(bar)[XB_TMO])) break; if (_sp > XB_SPIN_CAP) { atomicAdd(&(bar)[XB_TMO], 1u); break; } } } } while (0)
; __device__ __forceinline__ void grid_barrier1(int wid_s, unsigned* bar, volatile unsigned* st) {
;     ...
;             xb_add(&bar[XB_XGEN(x)], 1u);
;             asm volatile("s_waitcnt vmcnt(0)" ::: "memory");
;         } else {
;             XB_SPIN(xb_ld(&bar[XB_XGEN(x)]) == gen, bar);
;             __builtin_amdgcn_fence(__ATOMIC_ACQUIRE, "agent");
;             asm volatile("s_waitcnt vmcnt(0)" ::: "memory");
;         }
;     }
;     __syncthreads();
; }
.LBB0_2364:
	s_or_b64 exec, exec, s[2:3]
	v_mov_b32_e32 v0, s25
	v_add_co_u32_e32 v0, vcc, 0x2000, v0
	v_mov_b32_e32 v1, s24
	s_nop 0
	v_addc_co_u32_e32 v1, vcc, 0, v1, vcc
	s_waitcnt vmcnt(0) lgkmcnt(0)
	flat_atomic_add v[0:1], v170 offset:1024
.LBB0_2365:
	s_or_b64 exec, exec, s[44:45]
	s_add_i32 s33, s33, 1
	s_cmp_lg_u32 s33, s0
	s_waitcnt lgkmcnt(0)
	s_barrier
	s_cbranch_scc0 .LBB0_2279

; __device__ __forceinline__ unsigned xb_ld(unsigned* p)              { return __hip_atomic_load(p, __ATOMIC_RELAXED, __HIP_MEMORY_SCOPE_AGENT); }
; __device__ __forceinline__ unsigned xb_add(unsigned* p, unsigned v) { return __hip_atomic_fetch_add(p, v, __ATOMIC_RELAXED, __HIP_MEMORY_SCOPE_AGENT); }
; #define XB_SPIN(cond, bar) do { unsigned _sp = 0; while (cond) { \
;     if ((++_sp & 255u) == 0u) { if (xb_ld(&(bar)[XB_TMO])) break; if (_sp > XB_SPIN_CAP) { atomicAdd(&(bar)[XB_TMO], 1u); break; } } } } while (0)
; __device__ __forceinline__ void grid_barrier1(int wid_s, unsigned* bar, volatile unsigned* st) {
;     ...
;             xb_add(&bar[XB_XGEN(x)], 1u);
;             asm volatile("s_waitcnt vmcnt(0)" ::: "memory");
;         } else {
;             XB_SPIN(xb_ld(&bar[XB_XGEN(x)]) == gen, bar);
;             __builtin_amdgcn_fence(__ATOMIC_ACQUIRE, "agent");
;             asm volatile("s_waitcnt vmcnt(0)" ::: "memory");
;         }
;     }
;     __syncthreads();
; }
.LBB0_2411:
	s_or_b64 exec, exec, s[2:3]
	v_mov_b32_e32 v0, s24
	v_add_co_u32_e32 v0, vcc, 0x2000, v0
	v_mov_b32_e32 v1, s19
	s_nop 0
	v_addc_co_u32_e32 v1, vcc, 0, v1, vcc
	s_waitcnt vmcnt(0) lgkmcnt(0)
	flat_atomic_add v[0:1], v170 offset:1024
.LBB0_2412:
	s_or_b64 exec, exec, s[44:45]
	s_add_i32 s18, s18, 1
	s_cmp_lg_u32 s18, s0
	s_waitcnt lgkmcnt(0)
	s_barrier
	s_cbranch_scc0 .LBB0_2456

; __device__ __forceinline__ int mk_tid(int wid_s) { int t = wid_s * 64 + (int)__builtin_amdgcn_mbcnt_hi(~0u, __builtin_amdgcn_mbcnt_lo(~0u, 0u)); asm volatile("" : "+v"(t)); return t; }
; __device__ __forceinline__ unsigned xb_ld(unsigned* p)              { return __hip_atomic_load(p, __ATOMIC_RELAXED, __HIP_MEMORY_SCOPE_AGENT); }
; __device__ __forceinline__ unsigned xb_add(unsigned* p, unsigned v) { return __hip_atomic_fetch_add(p, v, __ATOMIC_RELAXED, __HIP_MEMORY_SCOPE_AGENT); }
; __device__ __forceinline__ unsigned xb_xcc_id() { return (unsigned)__builtin_amdgcn_s_getreg((3 << 11) | 20) & 0xFu; }
; #define XB_SPIN(cond, bar) do { unsigned _sp = 0; while (cond) { \
;     if ((++_sp & 255u) == 0u) { if (xb_ld(&(bar)[XB_TMO])) break; if (_sp > XB_SPIN_CAP) { atomicAdd(&(bar)[XB_TMO], 1u); break; } } } } while (0)
; __device__ __forceinline__ void grid_barrier1(int wid_s, unsigned* bar, volatile unsigned* st) {
;     asm volatile("s_waitcnt vmcnt(0)" ::: "memory");
;     __syncthreads();
;     if (mk_tid(wid_s) == 0) {
;         const unsigned x = xb_xcc_id();
;         __builtin_amdgcn_s_waitcnt(0);
;         unsigned nloc = st[0], nx = st[1];
;         if (nloc == 0u) { xcd_barrier_complete(bar, x, nloc, nx); st[0] = nloc; st[1] = nx; }
;         const unsigned old = xb_add(&bar[XB_XSUB(x)], 1u);
;         const unsigned gen = old / nloc;
;         if (old + 1u == (gen + 1u) * nloc) {
;             __builtin_amdgcn_fence(__ATOMIC_RELEASE, "agent");
;             asm volatile("s_waitcnt vmcnt(0)" ::: "memory");
;             const unsigned og = xb_add(&bar[XB_TOP], 1u);
;             const unsigned tg = og / nx;
;             if (og + 1u == (tg + 1u) * nx) xb_add(&bar[XB_TOPGEN], 1u);
;             else XB_SPIN(xb_ld(&bar[XB_TOPGEN]) == tg, bar);
;             __builtin_amdgcn_fence(__ATOMIC_ACQUIRE, "agent");
;             xb_add(&bar[XB_XGEN(x)], 1u);
;             asm volatile("s_waitcnt vmcnt(0)" ::: "memory");
;         } else {
;             XB_SPIN(xb_ld(&bar[XB_XGEN(x)]) == gen, bar);
;             __builtin_amdgcn_fence(__ATOMIC_ACQUIRE, "agent");
;             asm volatile("s_waitcnt vmcnt(0)" ::: "memory");
;         }
;     }
;     __syncthreads();
; }
.LBB0_2893:
	s_or_b64 exec, exec, s[2:3]
	v_mov_b32_e32 v0, s25
	v_add_co_u32_e32 v0, vcc, 0x2000, v0
	v_mov_b32_e32 v1, s24
	s_nop 0
	v_addc_co_u32_e32 v1, vcc, 0, v1, vcc
	s_waitcnt vmcnt(0) lgkmcnt(0)
	flat_atomic_add v[0:1], v170 offset:1024
.LBB0_2894:
	s_or_b64 exec, exec, s[44:45]
	s_add_i32 s19, s19, 1
	s_cmp_lg_u32 s19, s18
	s_waitcnt lgkmcnt(0)
	s_barrier
	s_cbranch_scc0 .LBB0_2458
.LBB0_2895:
	s_waitcnt vmcnt(0)
	v_mov_b32_e32 v0, v169
	s_waitcnt vmcnt(0) lgkmcnt(0)
	s_barrier
	s_nop 0
	v_cmp_eq_u32_e32 vcc, 0, v0
	s_and_saveexec_b64 s[44:45], vcc
	s_cbranch_execz .LBB0_2894
	s_mov_b64 s[2:3], src_shared_base
	s_getreg_b32 s2, hwreg(HW_REG_XCC_ID, 0, 4)
	s_and_b32 s33, s2, 15
	s_add_i32 s37, 0, 0x222f0
	s_cmp_lg_u32 s37, -1
	s_cselect_b32 s2, s37, 0
	s_cselect_b32 s4, s3, 0
	s_add_i32 s36, 0, 0x222f4
	s_cmp_lg_u32 s36, -1
	v_mov_b32_e32 v0, s2
	v_mov_b32_e32 v1, s4
	s_cselect_b32 s2, s36, 0
	s_cselect_b32 s3, s3, 0
	s_waitcnt vmcnt(0) expcnt(0) lgkmcnt(0)
	ds_read_b32 v2, v0
	ds_read_b32 v0, v0 offset:4
	s_waitcnt lgkmcnt(0)
	v_cmp_eq_u32_e32 vcc, 0, v2
	s_and_saveexec_b64 s[46:47], vcc
	s_cbranch_execz .LBB0_2910
	s_mov_b32 s22, 1
	s_mov_b64 s[2:3], 0
	s_branch .LBB0_2900

; __device__ __forceinline__ int mk_tid(int wid_s) { int t = wid_s * 64 + (int)__builtin_amdgcn_mbcnt_hi(~0u, __builtin_amdgcn_mbcnt_lo(~0u, 0u)); asm volatile("" : "+v"(t)); return t; }
; __device__ __forceinline__ unsigned xb_ld(unsigned* p)              { return __hip_atomic_load(p, __ATOMIC_RELAXED, __HIP_MEMORY_SCOPE_AGENT); }
; __device__ __forceinline__ unsigned xb_add(unsigned* p, unsigned v) { return __hip_atomic_fetch_add(p, v, __ATOMIC_RELAXED, __HIP_MEMORY_SCOPE_AGENT); }
; __device__ __forceinline__ unsigned xb_xcc_id() { return (unsigned)__builtin_amdgcn_s_getreg((3 << 11) | 20) & 0xFu; }
; #define XB_SPIN(cond, bar) do { unsigned _sp = 0; while (cond) { \
;     if ((++_sp & 255u) == 0u) { if (xb_ld(&(bar)[XB_TMO])) break; if (_sp > XB_SPIN_CAP) { atomicAdd(&(bar)[XB_TMO], 1u); break; } } } } while (0)
; __device__ __forceinline__ void grid_barrier1(int wid_s, unsigned* bar, volatile unsigned* st) {
;     asm volatile("s_waitcnt vmcnt(0)" ::: "memory");
;     __syncthreads();
;     if (mk_tid(wid_s) == 0) {
;         const unsigned x = xb_xcc_id();
;         __builtin_amdgcn_s_waitcnt(0);
;         unsigned nloc = st[0], nx = st[1];
;         if (nloc == 0u) { xcd_barrier_complete(bar, x, nloc, nx); st[0] = nloc; st[1] = nx; }
;         const unsigned old = xb_add(&bar[XB_XSUB(x)], 1u);
;         const unsigned gen = old / nloc;
;         if (old + 1u == (gen + 1u) * nloc) {
;             __builtin_amdgcn_fence(__ATOMIC_RELEASE, "agent");
;             asm volatile("s_waitcnt vmcnt(0)" ::: "memory");
;             const unsigned og = xb_add(&bar[XB_TOP], 1u);
;             const unsigned tg = og / nx;
;             if (og + 1u == (tg + 1u) * nx) xb_add(&bar[XB_TOPGEN], 1u);
;             else XB_SPIN(xb_ld(&bar[XB_TOPGEN]) == tg, bar);
;             __builtin_amdgcn_fence(__ATOMIC_ACQUIRE, "agent");
;             xb_add(&bar[XB_XGEN(x)], 1u);
;             asm volatile("s_waitcnt vmcnt(0)" ::: "memory");
;         } else {
;             XB_SPIN(xb_ld(&bar[XB_XGEN(x)]) == gen, bar);
;             __builtin_amdgcn_fence(__ATOMIC_ACQUIRE, "agent");
;             asm volatile("s_waitcnt vmcnt(0)" ::: "memory");
;         }
;     }
;     __syncthreads();
; }
.LBB0_3056:
	s_or_b64 exec, exec, s[2:3]
	v_mov_b32_e32 v0, s25
	v_add_co_u32_e32 v0, vcc, 0x2000, v0
	v_mov_b32_e32 v1, s24
	s_nop 0
	v_addc_co_u32_e32 v1, vcc, 0, v1, vcc
	s_waitcnt vmcnt(0) lgkmcnt(0)
	flat_atomic_add v[0:1], v170 offset:1024
.LBB0_3057:
	s_or_b64 exec, exec, s[46:47]
	s_add_i32 s18, s18, 1
	s_cmp_lg_u32 s18, s0
	s_waitcnt lgkmcnt(0)
	s_barrier
	s_cbranch_scc0 .LBB0_2940
.LBB0_3058:
	s_waitcnt vmcnt(0)
	v_mov_b32_e32 v0, v169
	s_waitcnt vmcnt(0) lgkmcnt(0)
	s_barrier
	s_nop 0
	v_cmp_eq_u32_e32 vcc, 0, v0
	s_and_saveexec_b64 s[46:47], vcc
	s_cbranch_execz .LBB0_3057
	s_mov_b64 s[2:3], src_shared_base
	s_getreg_b32 s2, hwreg(HW_REG_XCC_ID, 0, 4)
	s_and_b32 s33, s2, 15
	s_add_i32 s37, 0, 0x222f0
	s_cmp_lg_u32 s37, -1
	s_cselect_b32 s2, s37, 0
	s_cselect_b32 s4, s3, 0
	s_add_i32 s36, 0, 0x222f4
	s_cmp_lg_u32 s36, -1
	v_mov_b32_e32 v0, s2
	v_mov_b32_e32 v1, s4
	s_cselect_b32 s2, s36, 0
	s_cselect_b32 s3, s3, 0
	s_waitcnt vmcnt(0) expcnt(0) lgkmcnt(0)
	ds_read_b32 v2, v0
	ds_read_b32 v0, v0 offset:4
	s_waitcnt lgkmcnt(0)
	v_cmp_eq_u32_e32 vcc, 0, v2
	s_and_saveexec_b64 s[56:57], vcc
	s_cbranch_execz .LBB0_3073
	s_mov_b32 s22, 1
	s_mov_b64 s[2:3], 0
	s_branch .LBB0_3063

; __device__ __forceinline__ unsigned xb_ld(unsigned* p)              { return __hip_atomic_load(p, __ATOMIC_RELAXED, __HIP_MEMORY_SCOPE_AGENT); }
; __device__ __forceinline__ unsigned xb_add(unsigned* p, unsigned v) { return __hip_atomic_fetch_add(p, v, __ATOMIC_RELAXED, __HIP_MEMORY_SCOPE_AGENT); }
; #define XB_SPIN(cond, bar) do { unsigned _sp = 0; while (cond) { \
;     if ((++_sp & 255u) == 0u) { if (xb_ld(&(bar)[XB_TMO])) break; if (_sp > XB_SPIN_CAP) { atomicAdd(&(bar)[XB_TMO], 1u); break; } } } } while (0)
; __device__ __forceinline__ void grid_barrier1(int wid_s, unsigned* bar, volatile unsigned* st) {
;     ...
;             xb_add(&bar[XB_XGEN(x)], 1u);
;             asm volatile("s_waitcnt vmcnt(0)" ::: "memory");
;         } else {
;             XB_SPIN(xb_ld(&bar[XB_XGEN(x)]) == gen, bar);
;             __builtin_amdgcn_fence(__ATOMIC_ACQUIRE, "agent");
;             asm volatile("s_waitcnt vmcnt(0)" ::: "memory");
;         }
;     }
;     __syncthreads();
; }
.LBB0_3103:
	s_or_b64 exec, exec, s[2:3]
	v_mov_b32_e32 v0, s24
	v_add_co_u32_e32 v0, vcc, 0x2000, v0
	v_mov_b32_e32 v1, s19
	s_nop 0
	v_addc_co_u32_e32 v1, vcc, 0, v1, vcc
	s_waitcnt vmcnt(0) lgkmcnt(0)
	flat_atomic_add v[0:1], v170 offset:1024
.LBB0_3104:
	s_or_b64 exec, exec, s[44:45]
	s_add_i32 s18, s18, 1
	s_cmp_lg_u32 s18, s0
	s_waitcnt lgkmcnt(0)
	s_barrier
	s_cbranch_scc1 .LBB0_3105
	s_getpc_b64 s[98:99]
